# attn queue: single-unit items (query block 63..4 one per item, size-descending) through the tuned first instance; second instance only for query blocks 1,0
# speedup vs baseline: 1.0305x; 1.0305x over previous
; __device__ __forceinline__ int fresh_tid(int wave_s) { unsigned m = ~0u; asm volatile("" : "+s"(m)); int t = wave_s * 64 + (int)__builtin_amdgcn_mbcnt_hi(m, __builtin_amdgcn_mbcnt_lo(m, 0u)); asm volatile("" : "+v"(t)); return t; }
; __global__ void __launch_bounds__(512, 2) hybrid_fwd(Ctx c) {
;     ...
;         for (int kx = 0; kx < 8; ++kx) {
;             const int xq = (x0 + kx) & 7;
;             for (;;) {
;                 if (fresh_tid(wave0) == 0) MISC[16] = atomicAdd(ctl + CW_XQ + 64 * xq, 1u);
;                 __syncthreads();
;                 const int it = (int)MISC[16];
;                 __syncthreads();
;                 if (it >= 128) break;
.LBB0_815:
	s_mov_b64 s[0:1], 0
	s_waitcnt vmcnt(63) expcnt(7) lgkmcnt(15)
	s_barrier
.Lq_skip_inst2:
	s_mov_b64 s[0:1], 0

; __device__ __forceinline__ int fresh_tid(int wave_s) { unsigned m = ~0u; asm volatile("" : "+s"(m)); int t = wave_s * 64 + (int)__builtin_amdgcn_mbcnt_hi(m, __builtin_amdgcn_mbcnt_lo(m, 0u)); asm volatile("" : "+v"(t)); return t; }
; __global__ void __launch_bounds__(512, 2) hybrid_fwd(Ctx c) {
;     ...
;             for (;;) {
;                 if (fresh_tid(wave0) == 0) MISC[16] = atomicAdd(ctl + CW_XQ + 64 * xq, 1u);
;                 __syncthreads();
;                 const int it = (int)MISC[16];
;                 __syncthreads();
;                 if (it >= 128) break;
;                 const int bh = 4 * xq + (it >> 5), pp = it & 31;
.LBB0_821:
	s_or_b64 exec, exec, s[0:1]
	s_waitcnt lgkmcnt(0)
	s_barrier
	ds_read_b32 v0, v204
	s_movk_i32 s0, 0xf7
	s_waitcnt lgkmcnt(0)
	s_barrier
	v_cmp_lt_i32_e32 vcc, s0, v0
	v_readfirstlane_b32 s45, v0
	s_mov_b64 s[0:1], -1
	s_cbranch_vccnz .LBB0_816
	s_mov_b32 s0, -1
	s_and_b32 s50, s45, 3
	v_mbcnt_lo_u32_b32 v0, s0, 0
	v_mbcnt_hi_u32_b32 v0, s0, v0
	s_add_i32 s44, s50, s79
	s_waitcnt vmcnt(3)
	v_add_u32_e32 v44, s33, v0
	s_and_b32 s80, s44, 7
	s_nop 0
	v_readfirstlane_b32 s51, v44
	v_cmp_gt_i32_e32 vcc, s66, v44
	s_and_saveexec_b64 s[0:1], vcc
	s_cbranch_execz .LBB0_832
	v_add_u32_e32 v0, 0xffffff80, v44
	v_sub_u32_e32 v2, 0x80, v44
	v_max_i32_e32 v0, v0, v2
	v_cmp_lt_u32_e32 vcc, 7, v0
	s_and_saveexec_b64 s[2:3], vcc
	s_cbranch_execz .LBB0_831
	v_cmp_lt_u32_e32 vcc, 11, v0
	v_mov_b32_e32 v2, 8
	s_and_saveexec_b64 s[16:17], vcc
	s_cbranch_execz .LBB0_830
	v_cmp_lt_u32_e32 vcc, 15, v0
	v_mov_b32_e32 v2, 9
	s_and_saveexec_b64 s[40:41], vcc
	s_cbranch_execz .LBB0_829
	v_cmp_lt_u32_e32 vcc, 22, v0
	v_mov_b32_e32 v2, 10
	s_and_saveexec_b64 s[42:43], vcc
	v_cmp_gt_u32_e32 vcc, s68, v0
	s_nop 1
	v_cndmask_b32_e64 v2, 15, 14, vcc
	v_cmp_lt_u32_e32 vcc, 63, v0
	s_nop 1
	v_cndmask_b32_e32 v2, 13, v2, vcc
	v_cmp_lt_u32_e32 vcc, 45, v0
	s_nop 1
	v_cndmask_b32_e32 v2, 12, v2, vcc
	v_cmp_lt_u32_e32 vcc, 31, v0
	s_nop 1
	v_cndmask_b32_e32 v2, 11, v2, vcc
	s_or_b64 exec, exec, s[42:43]

; __global__ void __launch_bounds__(512, 2) hybrid_fwd(Ctx c) {
;     ...
;                 attn_unit16<false>(c, lds, bh >> 3, bh & 7, 63 - pp, wave0);
;                 attn_unit16<false>(c, lds, bh >> 3, bh & 7, pp, wave0);
.LBB0_888:
	s_mov_b32 s0, -1
	s_waitcnt vmcnt(63) expcnt(7) lgkmcnt(15)
	s_barrier
	s_cmp_lt_u32 s56, 60
	s_cbranch_scc1 .Lq_skip_inst2
	s_sub_u32 s56, 61, s56
	s_nop 0
	v_mbcnt_lo_u32_b32 v0, s0, 0
	v_mbcnt_hi_u32_b32 v0, s0, v0
	v_add_u32_e32 v46, s33, v0
	s_nop 0
	v_readfirstlane_b32 s81, v46
	v_cmp_gt_i32_e32 vcc, s66, v46
	s_and_saveexec_b64 s[0:1], vcc
	s_cbranch_execz .LBB0_898
	v_add_u32_e32 v0, 0xffffff80, v46
	v_sub_u32_e32 v2, 0x80, v46
	v_max_i32_e32 v0, v0, v2
	v_cmp_lt_u32_e32 vcc, 7, v0
	s_and_saveexec_b64 s[2:3], vcc
	s_cbranch_execz .LBB0_897
	v_cmp_lt_u32_e32 vcc, 11, v0
	v_mov_b32_e32 v2, 8
	s_and_saveexec_b64 s[50:51], vcc
	s_cbranch_execz .LBB0_896
	v_cmp_lt_u32_e32 vcc, 15, v0
	v_mov_b32_e32 v2, 9
	s_and_saveexec_b64 s[60:61], vcc
	s_cbranch_execz .LBB0_895
	v_cmp_lt_u32_e32 vcc, 22, v0
	v_mov_b32_e32 v2, 10
	s_and_saveexec_b64 s[62:63], vcc
	v_cmp_gt_u32_e32 vcc, s68, v0
	s_nop 1
	v_cndmask_b32_e64 v2, 15, 14, vcc
	v_cmp_lt_u32_e32 vcc, 63, v0
	s_nop 1
	v_cndmask_b32_e32 v2, 13, v2, vcc
	v_cmp_lt_u32_e32 vcc, 45, v0
	s_nop 1
	v_cndmask_b32_e32 v2, 12, v2, vcc
	v_cmp_lt_u32_e32 vcc, 31, v0
	s_nop 1
	v_cndmask_b32_e32 v2, 11, v2, vcc
	s_or_b64 exec, exec, s[62:63]
